# SEL loop: per-element key-position compares only computed on the rare elementwise-mask path (not in every tile)
# speedup vs baseline: 1.0046x; 1.0014x over previous
.LBB0_630:
	s_lshl_b32 s74, s9, 7
	v_lshl_add_u64 v[66:67], v[182:183], 0, s[74:75]
	global_load_dwordx4 v[142:145], v[66:67], off
	global_load_dwordx4 v[138:141], v[66:67], off offset:2048
	global_load_dwordx4 v[134:137], v[66:67], off offset:1024
	global_load_dwordx4 v[130:133], v[66:67], off offset:3072
	s_waitcnt vmcnt(4)
	v_mfma_f32_32x32x16_bf16 v[66:81], v[118:121], v[82:85], 0
	v_mfma_f32_32x32x16_bf16 v[66:81], v[122:125], v[86:89], v[66:81]
	v_mfma_f32_32x32x16_bf16 v[66:81], v[126:129], v[90:93], v[66:81]
	v_mfma_f32_32x32x16_bf16 v[66:81], v[114:117], v[94:97], v[66:81]
	s_and_b64 vcc, exec, s[56:57]
	s_cbranch_vccnz .LBB0_632
	v_add_u32_e32 v186, s9, v173
	v_or_b32_e32 v202, 2, v186
	v_or_b32_e32 v200, 3, v186
	v_add_u32_e32 v192, 8, v186
	v_add_u32_e32 v201, 9, v186
	v_add_u32_e32 v193, 10, v186
	v_add_u32_e32 v191, 11, v186
	v_add_u32_e32 v190, 16, v186
	v_add_u32_e32 v189, 17, v186
	v_add_u32_e32 v188, 18, v186
	v_add_u32_e32 v187, 19, v186
	v_cmp_le_i32_e64 s[10:11], v186, v172
	v_cmp_lt_i32_e64 s[8:9], v186, v172
	v_cmp_le_i32_e64 s[30:31], v202, v172
	v_cmp_le_i32_e64 s[28:29], v200, v172
	v_cmp_le_i32_e64 s[26:27], v192, v172
	v_cmp_le_i32_e64 s[22:23], v201, v172
	v_cmp_le_i32_e64 s[18:19], v193, v172
	v_cmp_le_i32_e64 s[14:15], v191, v172
	v_cmp_le_i32_e64 s[12:13], v190, v172
	v_cmp_le_i32_e64 s[24:25], v189, v172
	v_cmp_le_i32_e64 s[20:21], v188, v172
	v_cmp_le_i32_e64 s[16:17], v187, v172
	s_and_b64 vcc, s[6:7], s[10:11]
	s_nop 6
	v_cndmask_b32_e32 v66, v248, v66, vcc
	s_and_b64 vcc, s[6:7], s[8:9]
	v_cndmask_b32_e32 v67, v248, v67, vcc
	s_and_b64 vcc, s[6:7], s[30:31]
	v_cndmask_b32_e32 v68, v248, v68, vcc
	s_and_b64 vcc, s[6:7], s[28:29]
	v_cndmask_b32_e32 v69, v248, v69, vcc
	s_and_b64 vcc, s[6:7], s[26:27]
	v_cndmask_b32_e32 v70, v248, v70, vcc
	s_and_b64 vcc, s[6:7], s[22:23]
	v_cndmask_b32_e32 v71, v248, v71, vcc
	s_and_b64 vcc, s[6:7], s[18:19]
	v_cndmask_b32_e32 v72, v248, v72, vcc
	s_and_b64 vcc, s[6:7], s[14:15]
	v_cndmask_b32_e32 v73, v248, v73, vcc
	s_and_b64 vcc, s[6:7], s[12:13]
	v_cndmask_b32_e32 v74, v248, v74, vcc
	s_and_b64 vcc, s[6:7], s[24:25]
	v_cndmask_b32_e32 v75, v248, v75, vcc
	s_and_b64 vcc, s[6:7], s[20:21]
	v_cndmask_b32_e32 v76, v248, v76, vcc
	s_and_b64 vcc, s[6:7], s[16:17]
	v_add_u32_e32 v0, 24, v186
	v_cndmask_b32_e32 v77, v248, v77, vcc
	v_cmp_le_i32_e32 vcc, v0, v172
	s_and_b64 vcc, s[6:7], vcc
	v_add_u32_e32 v0, 25, v186
	v_cndmask_b32_e32 v78, v248, v78, vcc
	v_cmp_le_i32_e32 vcc, v0, v172
	s_and_b64 vcc, s[6:7], vcc
	v_add_u32_e32 v0, 26, v186
	v_cndmask_b32_e32 v79, v248, v79, vcc
	v_cmp_le_i32_e32 vcc, v0, v172
	s_and_b64 vcc, s[6:7], vcc
	v_add_u32_e32 v0, 27, v186
	v_cndmask_b32_e32 v80, v248, v80, vcc
	v_cmp_le_i32_e32 vcc, v0, v172
	s_and_b64 vcc, s[6:7], vcc
	s_nop 0
	v_cndmask_b32_e32 v81, v248, v81, vcc
.LBB0_632:
	s_nop 9
	v_max_f32_e32 v0, v67, v67
	v_max_f32_e32 v196, v66, v66
	v_max_f32_e32 v0, v196, v0
	v_max3_f32 v0, v0, v68, v69
	v_max3_f32 v0, v0, v70, v71
	v_max3_f32 v0, v0, v72, v73
	v_max3_f32 v0, v0, v74, v75
	v_max3_f32 v0, v0, v76, v77
	v_max3_f32 v0, v0, v78, v79
	v_max3_f32 v0, v0, v80, v81
	v_cndmask_b32_e64 v0, v248, v0, s[6:7]
	v_mov_b32_e32 v196, v0
	s_nop 1
	v_permlane32_swap_b32_e32 v0, v196
	v_max_f32_e32 v196, v196, v196
	v_max_f32_e32 v0, v0, v0
	v_max_f32_e32 v0, v0, v196
	v_mul_f32_e32 v0, 0x3e38aa3b, v0
	v_max_f32_e32 v196, v203, v203
	v_max_f32_e32 v0, v196, v0
	v_sub_f32_e32 v196, v0, v203
	v_cmp_lt_f32_e32 vcc, s67, v196
	s_cbranch_vccz .LBB0_634
	v_sub_f32_e32 v196, v203, v0
	v_exp_f32_e32 v204, v196
	s_nop 0
	v_mul_f32_e32 v151, v151, v204
	v_pk_mul_f32 v[64:65], v[64:65], v[204:205] op_sel_hi:[1,0]
	v_pk_mul_f32 v[62:63], v[62:63], v[204:205] op_sel_hi:[1,0]
	v_pk_mul_f32 v[60:61], v[60:61], v[204:205] op_sel_hi:[1,0]
	v_pk_mul_f32 v[58:59], v[58:59], v[204:205] op_sel_hi:[1,0]
	v_pk_mul_f32 v[56:57], v[56:57], v[204:205] op_sel_hi:[1,0]
	v_pk_mul_f32 v[54:55], v[54:55], v[204:205] op_sel_hi:[1,0]
	v_pk_mul_f32 v[52:53], v[52:53], v[204:205] op_sel_hi:[1,0]
	v_pk_mul_f32 v[50:51], v[50:51], v[204:205] op_sel_hi:[1,0]
	v_pk_mul_f32 v[48:49], v[48:49], v[204:205] op_sel_hi:[1,0]
	v_pk_mul_f32 v[46:47], v[46:47], v[204:205] op_sel_hi:[1,0]
	v_pk_mul_f32 v[44:45], v[44:45], v[204:205] op_sel_hi:[1,0]
	v_pk_mul_f32 v[42:43], v[42:43], v[204:205] op_sel_hi:[1,0]
	v_pk_mul_f32 v[40:41], v[40:41], v[204:205] op_sel_hi:[1,0]
	v_pk_mul_f32 v[38:39], v[38:39], v[204:205] op_sel_hi:[1,0]
	v_pk_mul_f32 v[36:37], v[36:37], v[204:205] op_sel_hi:[1,0]
	v_pk_mul_f32 v[34:35], v[34:35], v[204:205] op_sel_hi:[1,0]
	s_branch .LBB0_635
